# P3 epilogue: rolling residual prefetch with counted vmcnt; P6 epilogue: hoisted loads + lane-permuted 64B stores
# speedup vs baseline: 1.0043x; 1.0043x over previous
.LBB0_887:
	s_lshl_b32 s7, s24, 8
	v_lshl_or_b32 v146, s6, 8, v150
	v_lshlrev_b32_e32 v250, 1, v146
	v_add_u32_e32 v242, s7, v148
	v_lshl_add_u32 v220, v242, 12, v250
	v_mov_b32_e32 v221, 0
	v_lshl_add_u64 v[220:221], v[220:221], 0, s[10:11]
	global_load_dwordx4 v[188:191], v[220:221], off
	global_load_dwordx4 v[192:195], v[220:221], off offset:256
	v_add_u32_e32 v243, s7, v151
	v_lshl_add_u32 v222, v243, 12, v250
	v_mov_b32_e32 v223, 0
	v_lshl_add_u64 v[222:223], v[222:223], 0, s[10:11]
	global_load_dwordx4 v[196:199], v[222:223], off
	global_load_dwordx4 v[200:203], v[222:223], off offset:256
	v_add_u32_e32 v244, s7, v152
	v_lshl_add_u32 v224, v244, 12, v250
	v_mov_b32_e32 v225, 0
	v_lshl_add_u64 v[224:225], v[224:225], 0, s[10:11]
	global_load_dwordx4 v[204:207], v[224:225], off
	global_load_dwordx4 v[208:211], v[224:225], off offset:256
	v_add_u32_e32 v245, s7, v153
	v_lshl_add_u32 v226, v245, 12, v250
	v_mov_b32_e32 v227, 0
	v_lshl_add_u64 v[226:227], v[226:227], 0, s[10:11]
	global_load_dwordx4 v[212:215], v[226:227], off
	global_load_dwordx4 v[216:219], v[226:227], off offset:256
	s_waitcnt vmcnt(7)
	v_lshlrev_b32_e32 v228, 16, v188
	v_and_b32_e32 v229, 0xffff0000, v188
	v_lshlrev_b32_e32 v230, 16, v189
	v_and_b32_e32 v231, 0xffff0000, v189
	v_lshlrev_b32_e32 v232, 16, v190
	v_and_b32_e32 v233, 0xffff0000, v190
	v_lshlrev_b32_e32 v234, 16, v191
	v_and_b32_e32 v235, 0xffff0000, v191
	v_pk_add_f32 v[228:229], v[124:125], v[228:229]
	v_pk_add_f32 v[230:231], v[126:127], v[230:231]
	v_pk_add_f32 v[232:233], v[120:121], v[232:233]
	v_pk_add_f32 v[234:235], v[122:123], v[234:235]
	v_cvt_pk_bf16_f32 v188, v228, v229
	v_cvt_pk_bf16_f32 v189, v230, v231
	v_cvt_pk_bf16_f32 v190, v232, v233
	v_cvt_pk_bf16_f32 v191, v234, v235
	v_mul_f32_e32 v236, v229, v229
	v_mul_f32_e32 v237, v231, v231
	v_mul_f32_e32 v238, v233, v233
	v_mul_f32_e32 v239, v235, v235
	v_fmac_f32_e32 v236, v228, v228
	v_fmac_f32_e32 v237, v230, v230
	v_fmac_f32_e32 v238, v232, v232
	v_fmac_f32_e32 v239, v234, v234
	global_store_dwordx4 v[220:221], v[188:191], off
	v_add_f32_e32 v236, v236, v237
	v_add_f32_e32 v238, v238, v239
	v_add_f32_e32 v240, v236, v238
	s_waitcnt vmcnt(7)
	v_lshlrev_b32_e32 v228, 16, v192
	v_and_b32_e32 v229, 0xffff0000, v192
	v_lshlrev_b32_e32 v230, 16, v193
	v_and_b32_e32 v231, 0xffff0000, v193
	v_lshlrev_b32_e32 v232, 16, v194
	v_and_b32_e32 v233, 0xffff0000, v194
	v_lshlrev_b32_e32 v234, 16, v195
	v_and_b32_e32 v235, 0xffff0000, v195
	v_pk_add_f32 v[228:229], v[116:117], v[228:229]
	v_pk_add_f32 v[230:231], v[118:119], v[230:231]
	v_pk_add_f32 v[232:233], v[112:113], v[232:233]
	v_pk_add_f32 v[234:235], v[114:115], v[234:235]
	v_cvt_pk_bf16_f32 v192, v228, v229
	v_cvt_pk_bf16_f32 v193, v230, v231
	v_cvt_pk_bf16_f32 v194, v232, v233
	v_cvt_pk_bf16_f32 v195, v234, v235
	v_mul_f32_e32 v236, v229, v229
	v_mul_f32_e32 v237, v231, v231
	v_mul_f32_e32 v238, v233, v233
	v_mul_f32_e32 v239, v235, v235
	v_fmac_f32_e32 v236, v228, v228
	v_fmac_f32_e32 v237, v230, v230
	v_fmac_f32_e32 v238, v232, v232
	v_fmac_f32_e32 v239, v234, v234
	global_store_dwordx4 v[220:221], v[192:195], off offset:256
	v_add_f32_e32 v236, v236, v237
	v_add_f32_e32 v238, v238, v239
	v_add_f32_e32 v236, v236, v238
	v_add_f32_e32 v240, v240, v236
	v_mov_b32_e32 v241, v240
	s_nop 1
	v_permlane16_swap_b32_e32 v240, v241
	v_add_f32_e32 v240, v240, v241
	v_mov_b32_e32 v241, v240
	s_nop 1
	v_permlane32_swap_b32_e32 v240, v241
	s_and_saveexec_b64 s[24:25], s[0:1]
	v_add_f32_e32 v240, v240, v241
	ds_write_b32 v159, v240
	s_or_b64 exec, exec, s[24:25]
	v_add_u32_e32 v246, s7, v154
	v_lshl_add_u32 v220, v246, 12, v250
	v_mov_b32_e32 v221, 0
	v_lshl_add_u64 v[220:221], v[220:221], 0, s[10:11]
	global_load_dwordx4 v[188:191], v[220:221], off
	global_load_dwordx4 v[192:195], v[220:221], off offset:256
	s_waitcnt vmcnt(9)
	v_lshlrev_b32_e32 v228, 16, v196
	v_and_b32_e32 v229, 0xffff0000, v196
	v_lshlrev_b32_e32 v230, 16, v197
	v_and_b32_e32 v231, 0xffff0000, v197
	v_lshlrev_b32_e32 v232, 16, v198
	v_and_b32_e32 v233, 0xffff0000, v198
	v_lshlrev_b32_e32 v234, 16, v199
	v_and_b32_e32 v235, 0xffff0000, v199
	v_pk_add_f32 v[228:229], v[108:109], v[228:229]
	v_pk_add_f32 v[230:231], v[110:111], v[230:231]
	v_pk_add_f32 v[232:233], v[104:105], v[232:233]
	v_pk_add_f32 v[234:235], v[106:107], v[234:235]
	v_cvt_pk_bf16_f32 v196, v228, v229
	v_cvt_pk_bf16_f32 v197, v230, v231
	v_cvt_pk_bf16_f32 v198, v232, v233
	v_cvt_pk_bf16_f32 v199, v234, v235
	v_mul_f32_e32 v236, v229, v229
	v_mul_f32_e32 v237, v231, v231
	v_mul_f32_e32 v238, v233, v233
	v_mul_f32_e32 v239, v235, v235
	v_fmac_f32_e32 v236, v228, v228
	v_fmac_f32_e32 v237, v230, v230
	v_fmac_f32_e32 v238, v232, v232
	v_fmac_f32_e32 v239, v234, v234
	global_store_dwordx4 v[222:223], v[196:199], off
	v_add_f32_e32 v236, v236, v237
	v_add_f32_e32 v238, v238, v239
	v_add_f32_e32 v240, v236, v238
	s_waitcnt vmcnt(9)
	v_lshlrev_b32_e32 v228, 16, v200
	v_and_b32_e32 v229, 0xffff0000, v200
	v_lshlrev_b32_e32 v230, 16, v201
	v_and_b32_e32 v231, 0xffff0000, v201
	v_lshlrev_b32_e32 v232, 16, v202
	v_and_b32_e32 v233, 0xffff0000, v202
	v_lshlrev_b32_e32 v234, 16, v203
	v_and_b32_e32 v235, 0xffff0000, v203
	v_pk_add_f32 v[228:229], v[100:101], v[228:229]
	v_pk_add_f32 v[230:231], v[102:103], v[230:231]
	v_pk_add_f32 v[232:233], v[96:97], v[232:233]
	v_pk_add_f32 v[234:235], v[98:99], v[234:235]
	v_cvt_pk_bf16_f32 v200, v228, v229
	v_cvt_pk_bf16_f32 v201, v230, v231
	v_cvt_pk_bf16_f32 v202, v232, v233
	v_cvt_pk_bf16_f32 v203, v234, v235
	v_mul_f32_e32 v236, v229, v229
	v_mul_f32_e32 v237, v231, v231
	v_mul_f32_e32 v238, v233, v233
	v_mul_f32_e32 v239, v235, v235
	v_fmac_f32_e32 v236, v228, v228
	v_fmac_f32_e32 v237, v230, v230
	v_fmac_f32_e32 v238, v232, v232
	v_fmac_f32_e32 v239, v234, v234
	global_store_dwordx4 v[222:223], v[200:203], off offset:256
	v_add_f32_e32 v236, v236, v237
	v_add_f32_e32 v238, v238, v239
	v_add_f32_e32 v236, v236, v238
	v_add_f32_e32 v240, v240, v236
	v_mov_b32_e32 v241, v240
	s_nop 1
	v_permlane16_swap_b32_e32 v240, v241
	v_add_f32_e32 v240, v240, v241
	v_mov_b32_e32 v241, v240
	s_nop 1
	v_permlane32_swap_b32_e32 v240, v241
	s_and_saveexec_b64 s[24:25], s[0:1]
	v_add_f32_e32 v240, v240, v241
	ds_write_b32 v161, v240
	s_or_b64 exec, exec, s[24:25]
	v_add_u32_e32 v247, s7, v155
	v_lshl_add_u32 v222, v247, 12, v250
	v_mov_b32_e32 v223, 0
	v_lshl_add_u64 v[222:223], v[222:223], 0, s[10:11]
	global_load_dwordx4 v[196:199], v[222:223], off
	global_load_dwordx4 v[200:203], v[222:223], off offset:256
	s_waitcnt vmcnt(11)
	v_lshlrev_b32_e32 v228, 16, v204
	v_and_b32_e32 v229, 0xffff0000, v204
	v_lshlrev_b32_e32 v230, 16, v205
	v_and_b32_e32 v231, 0xffff0000, v205
	v_lshlrev_b32_e32 v232, 16, v206
	v_and_b32_e32 v233, 0xffff0000, v206
	v_lshlrev_b32_e32 v234, 16, v207
	v_and_b32_e32 v235, 0xffff0000, v207
	v_pk_add_f32 v[228:229], v[92:93], v[228:229]
	v_pk_add_f32 v[230:231], v[94:95], v[230:231]
	v_pk_add_f32 v[232:233], v[88:89], v[232:233]
	v_pk_add_f32 v[234:235], v[90:91], v[234:235]
	v_cvt_pk_bf16_f32 v204, v228, v229
	v_cvt_pk_bf16_f32 v205, v230, v231
	v_cvt_pk_bf16_f32 v206, v232, v233
	v_cvt_pk_bf16_f32 v207, v234, v235
	v_mul_f32_e32 v236, v229, v229
	v_mul_f32_e32 v237, v231, v231
	v_mul_f32_e32 v238, v233, v233
	v_mul_f32_e32 v239, v235, v235
	v_fmac_f32_e32 v236, v228, v228
	v_fmac_f32_e32 v237, v230, v230
	v_fmac_f32_e32 v238, v232, v232
	v_fmac_f32_e32 v239, v234, v234
	global_store_dwordx4 v[224:225], v[204:207], off
	v_add_f32_e32 v236, v236, v237
	v_add_f32_e32 v238, v238, v239
	v_add_f32_e32 v240, v236, v238
	s_waitcnt vmcnt(11)
	v_lshlrev_b32_e32 v228, 16, v208
	v_and_b32_e32 v229, 0xffff0000, v208
	v_lshlrev_b32_e32 v230, 16, v209
	v_and_b32_e32 v231, 0xffff0000, v209
	v_lshlrev_b32_e32 v232, 16, v210
	v_and_b32_e32 v233, 0xffff0000, v210
	v_lshlrev_b32_e32 v234, 16, v211
	v_and_b32_e32 v235, 0xffff0000, v211
	v_pk_add_f32 v[228:229], v[84:85], v[228:229]
	v_pk_add_f32 v[230:231], v[86:87], v[230:231]
	v_pk_add_f32 v[232:233], v[80:81], v[232:233]
	v_pk_add_f32 v[234:235], v[82:83], v[234:235]
	v_cvt_pk_bf16_f32 v208, v228, v229
	v_cvt_pk_bf16_f32 v209, v230, v231
	v_cvt_pk_bf16_f32 v210, v232, v233
	v_cvt_pk_bf16_f32 v211, v234, v235
	v_mul_f32_e32 v236, v229, v229
	v_mul_f32_e32 v237, v231, v231
	v_mul_f32_e32 v238, v233, v233
	v_mul_f32_e32 v239, v235, v235
	v_fmac_f32_e32 v236, v228, v228
	v_fmac_f32_e32 v237, v230, v230
	v_fmac_f32_e32 v238, v232, v232
	v_fmac_f32_e32 v239, v234, v234
	global_store_dwordx4 v[224:225], v[208:211], off offset:256
	v_add_f32_e32 v236, v236, v237
	v_add_f32_e32 v238, v238, v239
	v_add_f32_e32 v236, v236, v238
	v_add_f32_e32 v240, v240, v236
	v_mov_b32_e32 v241, v240
	s_nop 1
	v_permlane16_swap_b32_e32 v240, v241
	v_add_f32_e32 v240, v240, v241
	v_mov_b32_e32 v241, v240
	s_nop 1
	v_permlane32_swap_b32_e32 v240, v241
	s_and_saveexec_b64 s[24:25], s[0:1]
	v_add_f32_e32 v240, v240, v241
	ds_write_b32 v163, v240
	s_or_b64 exec, exec, s[24:25]
	v_add_u32_e32 v248, s7, v156
	v_lshl_add_u32 v224, v248, 12, v250
	v_mov_b32_e32 v225, 0
	v_lshl_add_u64 v[224:225], v[224:225], 0, s[10:11]
	global_load_dwordx4 v[204:207], v[224:225], off
	global_load_dwordx4 v[208:211], v[224:225], off offset:256
	s_waitcnt vmcnt(13)
	v_lshlrev_b32_e32 v228, 16, v212
	v_and_b32_e32 v229, 0xffff0000, v212
	v_lshlrev_b32_e32 v230, 16, v213
	v_and_b32_e32 v231, 0xffff0000, v213
	v_lshlrev_b32_e32 v232, 16, v214
	v_and_b32_e32 v233, 0xffff0000, v214
	v_lshlrev_b32_e32 v234, 16, v215
	v_and_b32_e32 v235, 0xffff0000, v215
	v_pk_add_f32 v[228:229], v[76:77], v[228:229]
	v_pk_add_f32 v[230:231], v[78:79], v[230:231]
	v_pk_add_f32 v[232:233], v[72:73], v[232:233]
	v_pk_add_f32 v[234:235], v[74:75], v[234:235]
	v_cvt_pk_bf16_f32 v212, v228, v229
	v_cvt_pk_bf16_f32 v213, v230, v231
	v_cvt_pk_bf16_f32 v214, v232, v233
	v_cvt_pk_bf16_f32 v215, v234, v235
	v_mul_f32_e32 v236, v229, v229
	v_mul_f32_e32 v237, v231, v231
	v_mul_f32_e32 v238, v233, v233
	v_mul_f32_e32 v239, v235, v235
	v_fmac_f32_e32 v236, v228, v228
	v_fmac_f32_e32 v237, v230, v230
	v_fmac_f32_e32 v238, v232, v232
	v_fmac_f32_e32 v239, v234, v234
	global_store_dwordx4 v[226:227], v[212:215], off
	v_add_f32_e32 v236, v236, v237
	v_add_f32_e32 v238, v238, v239
	v_add_f32_e32 v240, v236, v238
	s_waitcnt vmcnt(13)
	v_lshlrev_b32_e32 v228, 16, v216
	v_and_b32_e32 v229, 0xffff0000, v216
	v_lshlrev_b32_e32 v230, 16, v217
	v_and_b32_e32 v231, 0xffff0000, v217
	v_lshlrev_b32_e32 v232, 16, v218
	v_and_b32_e32 v233, 0xffff0000, v218
	v_lshlrev_b32_e32 v234, 16, v219
	v_and_b32_e32 v235, 0xffff0000, v219
	v_pk_add_f32 v[228:229], v[68:69], v[228:229]
	v_pk_add_f32 v[230:231], v[70:71], v[230:231]
	v_pk_add_f32 v[232:233], v[64:65], v[232:233]
	v_pk_add_f32 v[234:235], v[66:67], v[234:235]
	v_cvt_pk_bf16_f32 v216, v228, v229
	v_cvt_pk_bf16_f32 v217, v230, v231
	v_cvt_pk_bf16_f32 v218, v232, v233
	v_cvt_pk_bf16_f32 v219, v234, v235
	v_mul_f32_e32 v236, v229, v229
	v_mul_f32_e32 v237, v231, v231
	v_mul_f32_e32 v238, v233, v233
	v_mul_f32_e32 v239, v235, v235
	v_fmac_f32_e32 v236, v228, v228
	v_fmac_f32_e32 v237, v230, v230
	v_fmac_f32_e32 v238, v232, v232
	v_fmac_f32_e32 v239, v234, v234
	global_store_dwordx4 v[226:227], v[216:219], off offset:256
	v_add_f32_e32 v236, v236, v237
	v_add_f32_e32 v238, v238, v239
	v_add_f32_e32 v236, v236, v238
	v_add_f32_e32 v240, v240, v236
	v_mov_b32_e32 v241, v240
	s_nop 1
	v_permlane16_swap_b32_e32 v240, v241
	v_add_f32_e32 v240, v240, v241
	v_mov_b32_e32 v241, v240
	s_nop 1
	v_permlane32_swap_b32_e32 v240, v241
	s_and_saveexec_b64 s[24:25], s[0:1]
	v_add_f32_e32 v240, v240, v241
	ds_write_b32 v165, v240
	s_or_b64 exec, exec, s[24:25]
	v_add_u32_e32 v249, s7, v157
	v_lshl_add_u32 v226, v249, 12, v250
	v_mov_b32_e32 v227, 0
	v_lshl_add_u64 v[226:227], v[226:227], 0, s[10:11]
	global_load_dwordx4 v[212:215], v[226:227], off
	global_load_dwordx4 v[216:219], v[226:227], off offset:256
	s_waitcnt vmcnt(13)
	v_lshlrev_b32_e32 v228, 16, v188
	v_and_b32_e32 v229, 0xffff0000, v188
	v_lshlrev_b32_e32 v230, 16, v189
	v_and_b32_e32 v231, 0xffff0000, v189
	v_lshlrev_b32_e32 v232, 16, v190
	v_and_b32_e32 v233, 0xffff0000, v190
	v_lshlrev_b32_e32 v234, 16, v191
	v_and_b32_e32 v235, 0xffff0000, v191
	v_pk_add_f32 v[228:229], v[60:61], v[228:229]
	v_pk_add_f32 v[230:231], v[62:63], v[230:231]
	v_pk_add_f32 v[232:233], v[56:57], v[232:233]
	v_pk_add_f32 v[234:235], v[58:59], v[234:235]
	v_cvt_pk_bf16_f32 v188, v228, v229
	v_cvt_pk_bf16_f32 v189, v230, v231
	v_cvt_pk_bf16_f32 v190, v232, v233
	v_cvt_pk_bf16_f32 v191, v234, v235
	v_mul_f32_e32 v236, v229, v229
	v_mul_f32_e32 v237, v231, v231
	v_mul_f32_e32 v238, v233, v233
	v_mul_f32_e32 v239, v235, v235
	v_fmac_f32_e32 v236, v228, v228
	v_fmac_f32_e32 v237, v230, v230
	v_fmac_f32_e32 v238, v232, v232
	v_fmac_f32_e32 v239, v234, v234
	global_store_dwordx4 v[220:221], v[188:191], off
	v_add_f32_e32 v236, v236, v237
	v_add_f32_e32 v238, v238, v239
	v_add_f32_e32 v240, v236, v238
	s_waitcnt vmcnt(13)
	v_lshlrev_b32_e32 v228, 16, v192
	v_and_b32_e32 v229, 0xffff0000, v192
	v_lshlrev_b32_e32 v230, 16, v193
	v_and_b32_e32 v231, 0xffff0000, v193
	v_lshlrev_b32_e32 v232, 16, v194
	v_and_b32_e32 v233, 0xffff0000, v194
	v_lshlrev_b32_e32 v234, 16, v195
	v_and_b32_e32 v235, 0xffff0000, v195
	v_pk_add_f32 v[228:229], v[52:53], v[228:229]
	v_pk_add_f32 v[230:231], v[54:55], v[230:231]
	v_pk_add_f32 v[232:233], v[48:49], v[232:233]
	v_pk_add_f32 v[234:235], v[50:51], v[234:235]
	v_cvt_pk_bf16_f32 v192, v228, v229
	v_cvt_pk_bf16_f32 v193, v230, v231
	v_cvt_pk_bf16_f32 v194, v232, v233
	v_cvt_pk_bf16_f32 v195, v234, v235
	v_mul_f32_e32 v236, v229, v229
	v_mul_f32_e32 v237, v231, v231
	v_mul_f32_e32 v238, v233, v233
	v_mul_f32_e32 v239, v235, v235
	v_fmac_f32_e32 v236, v228, v228
	v_fmac_f32_e32 v237, v230, v230
	v_fmac_f32_e32 v238, v232, v232
	v_fmac_f32_e32 v239, v234, v234
	global_store_dwordx4 v[220:221], v[192:195], off offset:256
	v_add_f32_e32 v236, v236, v237
	v_add_f32_e32 v238, v238, v239
	v_add_f32_e32 v236, v236, v238
	v_add_f32_e32 v240, v240, v236
	v_mov_b32_e32 v241, v240
	s_nop 1
	v_permlane16_swap_b32_e32 v240, v241
	v_add_f32_e32 v240, v240, v241
	v_mov_b32_e32 v241, v240
	s_nop 1
	v_permlane32_swap_b32_e32 v240, v241
	s_and_saveexec_b64 s[24:25], s[0:1]
	v_add_f32_e32 v240, v240, v241
	ds_write_b32 v167, v240
	s_or_b64 exec, exec, s[24:25]
	s_waitcnt vmcnt(11)
	v_lshlrev_b32_e32 v228, 16, v196
	v_and_b32_e32 v229, 0xffff0000, v196
	v_lshlrev_b32_e32 v230, 16, v197
	v_and_b32_e32 v231, 0xffff0000, v197
	v_lshlrev_b32_e32 v232, 16, v198
	v_and_b32_e32 v233, 0xffff0000, v198
	v_lshlrev_b32_e32 v234, 16, v199
	v_and_b32_e32 v235, 0xffff0000, v199
	v_pk_add_f32 v[228:229], v[44:45], v[228:229]
	v_pk_add_f32 v[230:231], v[46:47], v[230:231]
	v_pk_add_f32 v[232:233], v[40:41], v[232:233]
	v_pk_add_f32 v[234:235], v[42:43], v[234:235]
	v_cvt_pk_bf16_f32 v196, v228, v229
	v_cvt_pk_bf16_f32 v197, v230, v231
	v_cvt_pk_bf16_f32 v198, v232, v233
	v_cvt_pk_bf16_f32 v199, v234, v235
	v_mul_f32_e32 v236, v229, v229
	v_mul_f32_e32 v237, v231, v231
	v_mul_f32_e32 v238, v233, v233
	v_mul_f32_e32 v239, v235, v235
	v_fmac_f32_e32 v236, v228, v228
	v_fmac_f32_e32 v237, v230, v230
	v_fmac_f32_e32 v238, v232, v232
	v_fmac_f32_e32 v239, v234, v234
	global_store_dwordx4 v[222:223], v[196:199], off
	v_add_f32_e32 v236, v236, v237
	v_add_f32_e32 v238, v238, v239
	v_add_f32_e32 v240, v236, v238
	s_waitcnt vmcnt(11)
	v_lshlrev_b32_e32 v228, 16, v200
	v_and_b32_e32 v229, 0xffff0000, v200
	v_lshlrev_b32_e32 v230, 16, v201
	v_and_b32_e32 v231, 0xffff0000, v201
	v_lshlrev_b32_e32 v232, 16, v202
	v_and_b32_e32 v233, 0xffff0000, v202
	v_lshlrev_b32_e32 v234, 16, v203
	v_and_b32_e32 v235, 0xffff0000, v203
	v_pk_add_f32 v[228:229], v[36:37], v[228:229]
	v_pk_add_f32 v[230:231], v[38:39], v[230:231]
	v_pk_add_f32 v[232:233], v[32:33], v[232:233]
	v_pk_add_f32 v[234:235], v[34:35], v[234:235]
	v_cvt_pk_bf16_f32 v200, v228, v229
	v_cvt_pk_bf16_f32 v201, v230, v231
	v_cvt_pk_bf16_f32 v202, v232, v233
	v_cvt_pk_bf16_f32 v203, v234, v235
	v_mul_f32_e32 v236, v229, v229
	v_mul_f32_e32 v237, v231, v231
	v_mul_f32_e32 v238, v233, v233
	v_mul_f32_e32 v239, v235, v235
	v_fmac_f32_e32 v236, v228, v228
	v_fmac_f32_e32 v237, v230, v230
	v_fmac_f32_e32 v238, v232, v232
	v_fmac_f32_e32 v239, v234, v234
	global_store_dwordx4 v[222:223], v[200:203], off offset:256
	v_add_f32_e32 v236, v236, v237
	v_add_f32_e32 v238, v238, v239
	v_add_f32_e32 v236, v236, v238
	v_add_f32_e32 v240, v240, v236
	v_mov_b32_e32 v241, v240
	s_nop 1
	v_permlane16_swap_b32_e32 v240, v241
	v_add_f32_e32 v240, v240, v241
	v_mov_b32_e32 v241, v240
	s_nop 1
	v_permlane32_swap_b32_e32 v240, v241
	s_and_saveexec_b64 s[24:25], s[0:1]
	v_add_f32_e32 v240, v240, v241
	ds_write_b32 v169, v240
	s_or_b64 exec, exec, s[24:25]
	s_waitcnt vmcnt(9)
	v_lshlrev_b32_e32 v228, 16, v204
	v_and_b32_e32 v229, 0xffff0000, v204
	v_lshlrev_b32_e32 v230, 16, v205
	v_and_b32_e32 v231, 0xffff0000, v205
	v_lshlrev_b32_e32 v232, 16, v206
	v_and_b32_e32 v233, 0xffff0000, v206
	v_lshlrev_b32_e32 v234, 16, v207
	v_and_b32_e32 v235, 0xffff0000, v207
	v_pk_add_f32 v[228:229], v[28:29], v[228:229]
	v_pk_add_f32 v[230:231], v[30:31], v[230:231]
	v_pk_add_f32 v[232:233], v[24:25], v[232:233]
	v_pk_add_f32 v[234:235], v[26:27], v[234:235]
	v_cvt_pk_bf16_f32 v204, v228, v229
	v_cvt_pk_bf16_f32 v205, v230, v231
	v_cvt_pk_bf16_f32 v206, v232, v233
	v_cvt_pk_bf16_f32 v207, v234, v235
	v_mul_f32_e32 v236, v229, v229
	v_mul_f32_e32 v237, v231, v231
	v_mul_f32_e32 v238, v233, v233
	v_mul_f32_e32 v239, v235, v235
	v_fmac_f32_e32 v236, v228, v228
	v_fmac_f32_e32 v237, v230, v230
	v_fmac_f32_e32 v238, v232, v232
	v_fmac_f32_e32 v239, v234, v234
	global_store_dwordx4 v[224:225], v[204:207], off
	v_add_f32_e32 v236, v236, v237
	v_add_f32_e32 v238, v238, v239
	v_add_f32_e32 v240, v236, v238
	s_waitcnt vmcnt(9)
	v_lshlrev_b32_e32 v228, 16, v208
	v_and_b32_e32 v229, 0xffff0000, v208
	v_lshlrev_b32_e32 v230, 16, v209
	v_and_b32_e32 v231, 0xffff0000, v209
	v_lshlrev_b32_e32 v232, 16, v210
	v_and_b32_e32 v233, 0xffff0000, v210
	v_lshlrev_b32_e32 v234, 16, v211
	v_and_b32_e32 v235, 0xffff0000, v211
	v_pk_add_f32 v[228:229], v[20:21], v[228:229]
	v_pk_add_f32 v[230:231], v[22:23], v[230:231]
	v_pk_add_f32 v[232:233], v[16:17], v[232:233]
	v_pk_add_f32 v[234:235], v[18:19], v[234:235]
	v_cvt_pk_bf16_f32 v208, v228, v229
	v_cvt_pk_bf16_f32 v209, v230, v231
	v_cvt_pk_bf16_f32 v210, v232, v233
	v_cvt_pk_bf16_f32 v211, v234, v235
	v_mul_f32_e32 v236, v229, v229
	v_mul_f32_e32 v237, v231, v231
	v_mul_f32_e32 v238, v233, v233
	v_mul_f32_e32 v239, v235, v235
	v_fmac_f32_e32 v236, v228, v228
	v_fmac_f32_e32 v237, v230, v230
	v_fmac_f32_e32 v238, v232, v232
	v_fmac_f32_e32 v239, v234, v234
	global_store_dwordx4 v[224:225], v[208:211], off offset:256
	v_add_f32_e32 v236, v236, v237
	v_add_f32_e32 v238, v238, v239
	v_add_f32_e32 v236, v236, v238
	v_add_f32_e32 v240, v240, v236
	v_mov_b32_e32 v241, v240
	s_nop 1
	v_permlane16_swap_b32_e32 v240, v241
	v_add_f32_e32 v240, v240, v241
	v_mov_b32_e32 v241, v240
	s_nop 1
	v_permlane32_swap_b32_e32 v240, v241
	s_and_saveexec_b64 s[24:25], s[0:1]
	v_add_f32_e32 v240, v240, v241
	ds_write_b32 v171, v240
	s_or_b64 exec, exec, s[24:25]
	s_waitcnt vmcnt(7)
	v_lshlrev_b32_e32 v228, 16, v212
	v_and_b32_e32 v229, 0xffff0000, v212
	v_lshlrev_b32_e32 v230, 16, v213
	v_and_b32_e32 v231, 0xffff0000, v213
	v_lshlrev_b32_e32 v232, 16, v214
	v_and_b32_e32 v233, 0xffff0000, v214
	v_lshlrev_b32_e32 v234, 16, v215
	v_and_b32_e32 v235, 0xffff0000, v215
	v_pk_add_f32 v[228:229], v[12:13], v[228:229]
	v_pk_add_f32 v[230:231], v[14:15], v[230:231]
	v_pk_add_f32 v[232:233], v[8:9], v[232:233]
	v_pk_add_f32 v[234:235], v[10:11], v[234:235]
	v_cvt_pk_bf16_f32 v212, v228, v229
	v_cvt_pk_bf16_f32 v213, v230, v231
	v_cvt_pk_bf16_f32 v214, v232, v233
	v_cvt_pk_bf16_f32 v215, v234, v235
	v_mul_f32_e32 v236, v229, v229
	v_mul_f32_e32 v237, v231, v231
	v_mul_f32_e32 v238, v233, v233
	v_mul_f32_e32 v239, v235, v235
	v_fmac_f32_e32 v236, v228, v228
	v_fmac_f32_e32 v237, v230, v230
	v_fmac_f32_e32 v238, v232, v232
	v_fmac_f32_e32 v239, v234, v234
	global_store_dwordx4 v[226:227], v[212:215], off
	v_add_f32_e32 v236, v236, v237
	v_add_f32_e32 v238, v238, v239
	v_add_f32_e32 v240, v236, v238
	s_waitcnt vmcnt(7)
	v_lshlrev_b32_e32 v228, 16, v216
	v_and_b32_e32 v229, 0xffff0000, v216
	v_lshlrev_b32_e32 v230, 16, v217
	v_and_b32_e32 v231, 0xffff0000, v217
	v_lshlrev_b32_e32 v232, 16, v218
	v_and_b32_e32 v233, 0xffff0000, v218
	v_lshlrev_b32_e32 v234, 16, v219
	v_and_b32_e32 v235, 0xffff0000, v219
	v_pk_add_f32 v[228:229], v[4:5], v[228:229]
	v_pk_add_f32 v[230:231], v[6:7], v[230:231]
	v_pk_add_f32 v[232:233], v[0:1], v[232:233]
	v_pk_add_f32 v[234:235], v[2:3], v[234:235]
	v_cvt_pk_bf16_f32 v216, v228, v229
	v_cvt_pk_bf16_f32 v217, v230, v231
	v_cvt_pk_bf16_f32 v218, v232, v233
	v_cvt_pk_bf16_f32 v219, v234, v235
	v_mul_f32_e32 v236, v229, v229
	v_mul_f32_e32 v237, v231, v231
	v_mul_f32_e32 v238, v233, v233
	v_mul_f32_e32 v239, v235, v235
	v_fmac_f32_e32 v236, v228, v228
	v_fmac_f32_e32 v237, v230, v230
	v_fmac_f32_e32 v238, v232, v232
	v_fmac_f32_e32 v239, v234, v234
	global_store_dwordx4 v[226:227], v[216:219], off offset:256
	v_add_f32_e32 v236, v236, v237
	v_add_f32_e32 v238, v238, v239
	v_add_f32_e32 v236, v236, v238
	v_add_f32_e32 v240, v240, v236
	v_mov_b32_e32 v241, v240
	s_nop 1
	v_permlane16_swap_b32_e32 v240, v241
	v_add_f32_e32 v240, v240, v241
	v_mov_b32_e32 v241, v240
	s_nop 1
	v_permlane32_swap_b32_e32 v240, v241
	s_and_saveexec_b64 s[24:25], s[0:1]
	v_add_f32_e32 v240, v240, v241
	ds_write_b32 v173, v240
	s_or_b64 exec, exec, s[24:25]
	v_mov_b32_e32 v144, v242
	v_mov_b32_e32 v145, 0
	v_mov_b32_e32 v112, v243
	v_mov_b32_e32 v113, 0
	v_mov_b32_e32 v96, v244
	v_mov_b32_e32 v97, 0
	v_mov_b32_e32 v80, v245
	v_mov_b32_e32 v81, 0
	v_mov_b32_e32 v64, v246
	v_mov_b32_e32 v65, 0
	v_mov_b32_e32 v48, v247
	v_mov_b32_e32 v49, 0
	v_mov_b32_e32 v32, v248
	v_mov_b32_e32 v33, 0
	v_mov_b32_e32 v16, v249
	v_mov_b32_e32 v17, 0
	s_waitcnt lgkmcnt(0)
	s_barrier
	s_and_saveexec_b64 s[24:25], s[2:3]
	s_cbranch_execz .LBB0_905
	ds_read_b128 v[0:3], v158
	ds_read_b128 v[4:7], v160
	s_ashr_i32 s7, s6, 31
	s_lshl_b64 s[6:7], s[6:7], 2
	s_add_u32 s6, s44, s6
	s_waitcnt lgkmcnt(1)
	v_add_f32_e32 v0, v0, v1
	v_add_f32_e32 v1, v2, v3
	s_addc_u32 s7, s45, s7
	v_add_f32_e32 v2, v0, v1
	v_lshlrev_b64 v[0:1], 5, v[144:145]
	v_lshl_add_u64 v[0:1], s[6:7], 0, v[0:1]
	global_store_dword v[0:1], v2, off
	s_waitcnt lgkmcnt(0)
	v_add_f32_e32 v0, v4, v5
	v_add_f32_e32 v1, v6, v7
	v_add_f32_e32 v6, v0, v1
	ds_read_b128 v[0:3], v162
	v_lshlrev_b64 v[4:5], 5, v[112:113]
	v_lshl_add_u64 v[4:5], s[6:7], 0, v[4:5]
	global_store_dword v[4:5], v6, off
	ds_read_b128 v[4:7], v164
	s_waitcnt lgkmcnt(1)
	v_add_f32_e32 v0, v0, v1
	v_add_f32_e32 v1, v2, v3
	v_add_f32_e32 v2, v0, v1
	v_lshlrev_b64 v[0:1], 5, v[96:97]
	v_lshl_add_u64 v[0:1], s[6:7], 0, v[0:1]
	global_store_dword v[0:1], v2, off
	s_waitcnt lgkmcnt(0)
	v_add_f32_e32 v0, v4, v5
	v_add_f32_e32 v1, v6, v7
	v_add_f32_e32 v6, v0, v1
	ds_read_b128 v[0:3], v166
	v_lshlrev_b64 v[4:5], 5, v[80:81]
	v_lshl_add_u64 v[4:5], s[6:7], 0, v[4:5]
	global_store_dword v[4:5], v6, off
	ds_read_b128 v[4:7], v168
	s_waitcnt lgkmcnt(1)
	v_add_f32_e32 v0, v0, v1
	v_add_f32_e32 v1, v2, v3
	v_add_f32_e32 v2, v0, v1
	v_lshlrev_b64 v[0:1], 5, v[64:65]
	v_lshl_add_u64 v[0:1], s[6:7], 0, v[0:1]
	global_store_dword v[0:1], v2, off
	s_waitcnt lgkmcnt(0)
	v_add_f32_e32 v0, v4, v5
	v_add_f32_e32 v1, v6, v7
	v_add_f32_e32 v6, v0, v1
	ds_read_b128 v[0:3], v170
	v_lshlrev_b64 v[4:5], 5, v[48:49]
	v_lshl_add_u64 v[4:5], s[6:7], 0, v[4:5]
	global_store_dword v[4:5], v6, off
	ds_read_b128 v[4:7], v172
	s_waitcnt lgkmcnt(1)
	v_add_f32_e32 v0, v0, v1
	v_add_f32_e32 v1, v2, v3
	v_add_f32_e32 v2, v0, v1
	v_lshlrev_b64 v[0:1], 5, v[32:33]
	v_lshl_add_u64 v[0:1], s[6:7], 0, v[0:1]
	global_store_dword v[0:1], v2, off
	s_waitcnt lgkmcnt(0)
	v_add_f32_e32 v0, v4, v5
	v_add_f32_e32 v1, v6, v7
	v_add_f32_e32 v2, v0, v1
	v_lshlrev_b64 v[0:1], 5, v[16:17]
	v_lshl_add_u64 v[0:1], s[6:7], 0, v[0:1]
	global_store_dword v[0:1], v2, off
